# v8 + unaligned epilogues in FFN-in (no per-unit alignment barriers), baseline loop placement
# baseline (speedup 1.0000x reference)
; #define PG8_STAGE(bufoff, gbase, voff) do { _Pragma("unroll") for (int _i = 0; _i < 2; ++_i) \
;         __builtin_amdgcn_global_load_lds((const unsigned*)((const char*)(gbase) + (voff)[_i]), (LAS unsigned*)(lds + (bufoff) + ldsw + _i * 8192), 16, 0, 0); } while (0)
; #define PG8_LDA(dst, b, h) do { _Pragma("unroll") for (int m = 0; m < 4; ++m) _Pragma("unroll") for (int k = 0; k < 2; ++k) dst[m][k] = *(const LAS bf16x8*)(lds + PG8_SA(b, h) + aoff + m * 2048 + k * 1024); } while (0)
; #define PG8_LDB(dst, b, h) do { _Pragma("unroll") for (int n = 0; n < 2; ++n) _Pragma("unroll") for (int k = 0; k < 2; ++k) dst[n][k] = *(const LAS bf16x8*)(lds + PG8_SB(b, h) + boff + n * 2048 + k * 1024); } while (0)
; #define PG8_MMA(ai, bj, At, Bt) do { __builtin_amdgcn_s_setprio(1); _Pragma("unroll") for (int m = 0; m < 4; ++m) _Pragma("unroll") for (int n = 0; n < 2; ++n) _Pragma("unroll") for (int k = 0; k < 2; ++k) \
;         acc[ai][bj][m][n] = __builtin_amdgcn_mfma_f32_16x16x32_bf16(Bt[n][k], At[m][k], acc[ai][bj][m][n], 0, 0, 0); __builtin_amdgcn_s_setprio(0); } while (0)
; #define PG8_WAIT_V(n) asm volatile("s_waitcnt vmcnt(" #n ")" ::: "memory")
; #define PG8_WAIT_L(n) asm volatile("s_waitcnt lgkmcnt(" #n ")" ::: "memory")
; #define PG8_BAR __builtin_amdgcn_s_barrier()
; template <class Epi, class Sched>
; __device__ __forceinline__ void gemm_phase(LAS unsigned char* lds, const Gemm g, const Sched& S, const Epi& E) {
;     ...
;         for (int t = 0; t < nt; t += 2) {
;             const bool last = (t == nt - 2);
;             const char* a1 = cA + (size_t)(t + 1) * kstep;
;             const char* a2 = last ? nA : cA + (size_t)(t + 2) * kstep; const char* b2 = last ? nB : cB + (size_t)(t + 2) * kstep;
;             const char* a3 = a2 + kstep; const char* b3 = b2 + kstep;
;             if (last && has_next) S.a_ready(nxt);
;             PG8_LDB(B0, 0, 0); PG8_LDB(B1, 0, 1); PG8_SCHED; PG8_LDA(At, 0, 0); PG8_STAGE(PG8_SA(1, 1), a1 + hstepA, voffA);
;             PG8_WAIT_V(8); PG8_WAIT_L(0); PG8_BAR; PG8_MMA(0, 0, At, B0); PG8_MMA(0, 1, At, B1); PG8_BAR; PG8_SCHED;
;             PG8_LDA(At, 0, 1); PG8_STAGE(PG8_SB(0, 0), b2, voffB); PG8_STAGE(PG8_SB(0, 1), b2 + hstepB, voffB); PG8_STAGE(PG8_SA(0, 0), a2, voffA);
;             PG8_WAIT_V(8); PG8_WAIT_L(0); PG8_BAR; PG8_MMA(1, 0, At, B0); PG8_MMA(1, 1, At, B1); PG8_BAR; PG8_SCHED;
.LBB0_137:
	s_add_u32 s28, s26, 0xfff80080
	s_addc_u32 s29, s27, -1
	s_add_i32 s60, 0, 0x10000
	s_cmp_eq_u32 s59, 28
	s_cselect_b32 s41, s21, s29
	s_cselect_b32 s40, s55, s28
	s_cselect_b32 s29, s19, s58
	s_cselect_b32 s28, s56, s57
	s_add_i32 s62, 0, 0x14000
	v_add_u32_e32 v154, s60, v159
	v_add_u32_e32 v174, s62, v159
	ds_read_b128 v[142:145], v154
	ds_read_b128 v[146:149], v154 offset:1024
	ds_read_b128 v[150:153], v154 offset:2048
	ds_read_b128 v[154:157], v154 offset:3072
	ds_read_b128 v[162:165], v174
	ds_read_b128 v[166:169], v174 offset:1024
	ds_read_b128 v[170:173], v174 offset:2048
	ds_read_b128 v[174:177], v174 offset:3072
	v_lshl_add_u64 v[224:225], s[26:27], 0, v[138:139]
	s_add_i32 m0, s46, 0xc000
	ds_read_b128 v[178:181], v161
	ds_read_b128 v[182:185], v161 offset:1024
	ds_read_b128 v[186:189], v161 offset:2048
	ds_read_b128 v[190:193], v161 offset:3072
	ds_read_b128 v[194:197], v161 offset:4096
	ds_read_b128 v[212:215], v161 offset:5120
	ds_read_b128 v[216:219], v161 offset:6144
	ds_read_b128 v[220:223], v161 offset:7168
	global_load_lds_dwordx4 v[224:225], off
	v_lshl_add_u64 v[224:225], s[26:27], 0, v[140:141]
	s_add_i32 m0, s46, 0xe000
	s_nop 0
	global_load_lds_dwordx4 v[224:225], off
	s_waitcnt vmcnt(8)
	s_waitcnt lgkmcnt(0)
	s_barrier
	s_setprio 1
	s_waitcnt lgkmcnt(0)
	v_mfma_f32_16x16x32_bf16 v[130:133], v[142:145], v[178:181], v[130:133]
	v_mfma_f32_16x16x32_bf16 v[122:125], v[150:153], v[178:181], v[122:125]
	v_mfma_f32_16x16x32_bf16 v[114:117], v[142:145], v[186:189], v[114:117]
	v_mfma_f32_16x16x32_bf16 v[106:109], v[150:153], v[186:189], v[106:109]
	v_mfma_f32_16x16x32_bf16 v[98:101], v[142:145], v[194:197], v[98:101]
	v_mfma_f32_16x16x32_bf16 v[90:93], v[150:153], v[194:197], v[90:93]
	v_mfma_f32_16x16x32_bf16 v[82:85], v[142:145], v[216:219], v[82:85]
	v_mfma_f32_16x16x32_bf16 v[74:77], v[150:153], v[216:219], v[74:77]
	v_mfma_f32_16x16x32_bf16 v[130:133], v[146:149], v[182:185], v[130:133]
	v_mfma_f32_16x16x32_bf16 v[122:125], v[154:157], v[182:185], v[122:125]
	v_mfma_f32_16x16x32_bf16 v[114:117], v[146:149], v[190:193], v[114:117]
	v_mfma_f32_16x16x32_bf16 v[106:109], v[154:157], v[190:193], v[106:109]
	v_mfma_f32_16x16x32_bf16 v[98:101], v[146:149], v[212:215], v[98:101]
	v_mfma_f32_16x16x32_bf16 v[90:93], v[154:157], v[212:215], v[90:93]
	v_mfma_f32_16x16x32_bf16 v[82:85], v[146:149], v[220:223], v[82:85]
	v_mfma_f32_16x16x32_bf16 v[74:77], v[154:157], v[220:223], v[74:77]
	s_setprio 0
	s_setprio 1
	v_mfma_f32_16x16x32_bf16 v[126:129], v[162:165], v[178:181], v[126:129]
	v_mfma_f32_16x16x32_bf16 v[118:121], v[170:173], v[178:181], v[118:121]
	v_mfma_f32_16x16x32_bf16 v[110:113], v[162:165], v[186:189], v[110:113]
	v_mfma_f32_16x16x32_bf16 v[102:105], v[170:173], v[186:189], v[102:105]
	v_mfma_f32_16x16x32_bf16 v[94:97], v[162:165], v[194:197], v[94:97]
	v_mfma_f32_16x16x32_bf16 v[86:89], v[170:173], v[194:197], v[86:89]
	v_mfma_f32_16x16x32_bf16 v[78:81], v[162:165], v[216:219], v[78:81]
	v_mfma_f32_16x16x32_bf16 v[70:73], v[170:173], v[216:219], v[70:73]
	v_mfma_f32_16x16x32_bf16 v[126:129], v[166:169], v[182:185], v[126:129]
	v_mfma_f32_16x16x32_bf16 v[118:121], v[174:177], v[182:185], v[118:121]
	v_mfma_f32_16x16x32_bf16 v[110:113], v[166:169], v[190:193], v[110:113]
	v_mfma_f32_16x16x32_bf16 v[102:105], v[174:177], v[190:193], v[102:105]
	v_mfma_f32_16x16x32_bf16 v[94:97], v[166:169], v[212:215], v[94:97]
	v_mfma_f32_16x16x32_bf16 v[86:89], v[174:177], v[212:215], v[86:89]
	v_mfma_f32_16x16x32_bf16 v[78:81], v[166:169], v[220:223], v[78:81]
	v_mfma_f32_16x16x32_bf16 v[70:73], v[174:177], v[220:223], v[70:73]
	s_setprio 0
	s_barrier
	s_add_i32 s60, s60, s45
	v_lshl_add_u64 v[224:225], s[28:29], 0, v[4:5]
	s_mov_b32 m0, s60
	ds_read_b128 v[178:181], v161 offset:16384
	ds_read_b128 v[182:185], v161 offset:17408
	ds_read_b128 v[186:189], v161 offset:18432
	ds_read_b128 v[190:193], v161 offset:19456
	ds_read_b128 v[194:197], v161 offset:20480
	ds_read_b128 v[212:215], v161 offset:21504
	ds_read_b128 v[216:219], v161 offset:22528
	ds_read_b128 v[220:223], v161 offset:23552
	global_load_lds_dwordx4 v[224:225], off
	s_add_i32 m0, s60, 0x2000
	s_add_u32 s60, s28, 0x80000
	v_lshl_add_u64 v[226:227], s[28:29], 0, v[2:3]
	s_addc_u32 s61, s29, 0
	s_add_i32 s62, s62, s45
	global_load_lds_dwordx4 v[226:227], off
	v_lshl_add_u64 v[228:229], s[60:61], 0, v[4:5]
	s_mov_b32 m0, s62
	v_lshl_add_u64 v[230:231], s[40:41], 0, v[134:135]
	global_load_lds_dwordx4 v[228:229], off
	v_lshl_add_u64 v[228:229], s[60:61], 0, v[2:3]
	s_add_i32 m0, s62, 0x2000
	s_nop 0
	global_load_lds_dwordx4 v[228:229], off
	v_lshl_add_u64 v[228:229], s[40:41], 0, v[136:137]
	s_mov_b32 m0, s46
	s_nop 0
	global_load_lds_dwordx4 v[228:229], off
	s_mov_b32 m0, s47
	s_nop 0
	global_load_lds_dwordx4 v[230:231], off
	s_waitcnt vmcnt(8)
	s_waitcnt lgkmcnt(0)
	s_barrier
; #define PG8_STAGE(bufoff, gbase, voff) do { _Pragma("unroll") for (int _i = 0; _i < 2; ++_i) \
;         __builtin_amdgcn_global_load_lds((const unsigned*)((const char*)(gbase) + (voff)[_i]), (LAS unsigned*)(lds + (bufoff) + ldsw + _i * 8192), 16, 0, 0); } while (0)
; #define PG8_LDA(dst, b, h) do { _Pragma("unroll") for (int m = 0; m < 4; ++m) _Pragma("unroll") for (int k = 0; k < 2; ++k) dst[m][k] = *(const LAS bf16x8*)(lds + PG8_SA(b, h) + aoff + m * 2048 + k * 1024); } while (0)
; #define PG8_LDB(dst, b, h) do { _Pragma("unroll") for (int n = 0; n < 2; ++n) _Pragma("unroll") for (int k = 0; k < 2; ++k) dst[n][k] = *(const LAS bf16x8*)(lds + PG8_SB(b, h) + boff + n * 2048 + k * 1024); } while (0)
; #define PG8_MMA(ai, bj, At, Bt) do { __builtin_amdgcn_s_setprio(1); _Pragma("unroll") for (int m = 0; m < 4; ++m) _Pragma("unroll") for (int n = 0; n < 2; ++n) _Pragma("unroll") for (int k = 0; k < 2; ++k) \
;         acc[ai][bj][m][n] = __builtin_amdgcn_mfma_f32_16x16x32_bf16(Bt[n][k], At[m][k], acc[ai][bj][m][n], 0, 0, 0); __builtin_amdgcn_s_setprio(0); } while (0)
; #define PG8_WAIT_V(n) asm volatile("s_waitcnt vmcnt(" #n ")" ::: "memory")
; #define PG8_WAIT_L(n) asm volatile("s_waitcnt lgkmcnt(" #n ")" ::: "memory")
; #define PG8_BAR __builtin_amdgcn_s_barrier()
; #define PG8_SCHED __builtin_amdgcn_sched_barrier(0)
; template <class Epi, class Sched>
; __device__ __forceinline__ void gemm_phase(LAS unsigned char* lds, const Gemm g, const Sched& S, const Epi& E) {
;     ...
;             PG8_WAIT_V(8); PG8_WAIT_L(0); PG8_BAR; PG8_MMA(1, 0, At, B0); PG8_MMA(1, 1, At, B1); PG8_BAR; PG8_SCHED;
;             PG8_LDB(B0, 1, 0); PG8_LDB(B1, 1, 1); PG8_SCHED; PG8_LDA(At, 1, 0); PG8_STAGE(PG8_SA(0, 1), a2 + hstepA, voffA);
;             PG8_WAIT_V(8); PG8_WAIT_L(0); PG8_BAR; PG8_MMA(0, 0, At, B0); PG8_MMA(0, 1, At, B1); PG8_BAR; PG8_SCHED;
	s_setprio 1
	s_waitcnt lgkmcnt(0)
	v_mfma_f32_16x16x32_bf16 v[66:69], v[142:145], v[178:181], v[66:69]
	v_mfma_f32_16x16x32_bf16 v[58:61], v[150:153], v[178:181], v[58:61]
	v_mfma_f32_16x16x32_bf16 v[50:53], v[142:145], v[186:189], v[50:53]
	v_mfma_f32_16x16x32_bf16 v[42:45], v[150:153], v[186:189], v[42:45]
	v_mfma_f32_16x16x32_bf16 v[34:37], v[142:145], v[194:197], v[34:37]
	v_mfma_f32_16x16x32_bf16 v[26:29], v[150:153], v[194:197], v[26:29]
	v_mfma_f32_16x16x32_bf16 v[18:21], v[142:145], v[216:219], v[18:21]
	v_mfma_f32_16x16x32_bf16 v[10:13], v[150:153], v[216:219], v[10:13]
	v_mfma_f32_16x16x32_bf16 v[66:69], v[146:149], v[182:185], v[66:69]
	v_mfma_f32_16x16x32_bf16 v[58:61], v[154:157], v[182:185], v[58:61]
	v_mfma_f32_16x16x32_bf16 v[50:53], v[146:149], v[190:193], v[50:53]
	v_mfma_f32_16x16x32_bf16 v[42:45], v[154:157], v[190:193], v[42:45]
	v_mfma_f32_16x16x32_bf16 v[34:37], v[146:149], v[212:215], v[34:37]
	v_mfma_f32_16x16x32_bf16 v[26:29], v[154:157], v[212:215], v[26:29]
	v_mfma_f32_16x16x32_bf16 v[18:21], v[146:149], v[220:223], v[18:21]
	v_mfma_f32_16x16x32_bf16 v[10:13], v[154:157], v[220:223], v[10:13]
	s_setprio 0
	s_setprio 1
	v_mfma_f32_16x16x32_bf16 v[62:65], v[162:165], v[178:181], v[62:65]
	v_mfma_f32_16x16x32_bf16 v[54:57], v[170:173], v[178:181], v[54:57]
	v_mfma_f32_16x16x32_bf16 v[46:49], v[162:165], v[186:189], v[46:49]
	v_mfma_f32_16x16x32_bf16 v[38:41], v[170:173], v[186:189], v[38:41]
	v_mfma_f32_16x16x32_bf16 v[30:33], v[162:165], v[194:197], v[30:33]
	v_mfma_f32_16x16x32_bf16 v[22:25], v[170:173], v[194:197], v[22:25]
	v_mfma_f32_16x16x32_bf16 v[14:17], v[162:165], v[216:219], v[14:17]
	v_mfma_f32_16x16x32_bf16 v[6:9], v[170:173], v[216:219], v[6:9]
	v_mfma_f32_16x16x32_bf16 v[62:65], v[166:169], v[182:185], v[62:65]
	v_mfma_f32_16x16x32_bf16 v[54:57], v[174:177], v[182:185], v[54:57]
	v_mfma_f32_16x16x32_bf16 v[46:49], v[166:169], v[190:193], v[46:49]
	v_mfma_f32_16x16x32_bf16 v[38:41], v[174:177], v[190:193], v[38:41]
	v_mfma_f32_16x16x32_bf16 v[30:33], v[166:169], v[212:215], v[30:33]
	v_mfma_f32_16x16x32_bf16 v[22:25], v[174:177], v[212:215], v[22:25]
	v_mfma_f32_16x16x32_bf16 v[14:17], v[166:169], v[220:223], v[14:17]
	v_mfma_f32_16x16x32_bf16 v[6:9], v[174:177], v[220:223], v[6:9]
	s_setprio 0
	s_barrier
	s_add_i32 s60, 0, 0x18000
	s_add_i32 s61, 0, 0x1c000
	v_add_u32_e32 v154, s60, v159
	v_add_u32_e32 v174, s61, v159
	ds_read_b128 v[142:145], v154
	ds_read_b128 v[146:149], v154 offset:1024
	ds_read_b128 v[150:153], v154 offset:2048
	ds_read_b128 v[154:157], v154 offset:3072
	ds_read_b128 v[162:165], v174
	ds_read_b128 v[166:169], v174 offset:1024
	ds_read_b128 v[170:173], v174 offset:2048
	ds_read_b128 v[174:177], v174 offset:3072
	s_add_u32 s40, s40, 0x80000
	s_addc_u32 s41, s41, 0
	s_mov_b32 m0, s48
	v_lshl_add_u64 v[236:237], s[40:41], 0, v[136:137]
	ds_read_b128 v[178:181], v161 offset:32768
	ds_read_b128 v[182:185], v161 offset:33792
	ds_read_b128 v[186:189], v161 offset:34816
	ds_read_b128 v[190:193], v161 offset:35840
	ds_read_b128 v[194:197], v161 offset:36864
	ds_read_b128 v[212:215], v161 offset:37888
	ds_read_b128 v[216:219], v161 offset:38912
	ds_read_b128 v[220:223], v161 offset:39936
	global_load_lds_dwordx4 v[236:237], off
	v_lshl_add_u64 v[236:237], s[40:41], 0, v[134:135]
	s_mov_b32 m0, s49
	s_nop 0
	global_load_lds_dwordx4 v[236:237], off
	s_waitcnt vmcnt(8)
	s_waitcnt lgkmcnt(0)
	s_barrier
	s_setprio 1
	s_waitcnt lgkmcnt(0)
	v_mfma_f32_16x16x32_bf16 v[130:133], v[142:145], v[178:181], v[130:133]
	v_mfma_f32_16x16x32_bf16 v[122:125], v[150:153], v[178:181], v[122:125]
	v_mfma_f32_16x16x32_bf16 v[114:117], v[142:145], v[186:189], v[114:117]
	v_mfma_f32_16x16x32_bf16 v[106:109], v[150:153], v[186:189], v[106:109]
	v_mfma_f32_16x16x32_bf16 v[98:101], v[142:145], v[194:197], v[98:101]
	v_mfma_f32_16x16x32_bf16 v[90:93], v[150:153], v[194:197], v[90:93]
	v_mfma_f32_16x16x32_bf16 v[82:85], v[142:145], v[216:219], v[82:85]
	v_mfma_f32_16x16x32_bf16 v[74:77], v[150:153], v[216:219], v[74:77]
	v_mfma_f32_16x16x32_bf16 v[130:133], v[146:149], v[182:185], v[130:133]
	v_mfma_f32_16x16x32_bf16 v[122:125], v[154:157], v[182:185], v[122:125]
	v_mfma_f32_16x16x32_bf16 v[114:117], v[146:149], v[190:193], v[114:117]
	v_mfma_f32_16x16x32_bf16 v[106:109], v[154:157], v[190:193], v[106:109]
	v_mfma_f32_16x16x32_bf16 v[98:101], v[146:149], v[212:215], v[98:101]
	v_mfma_f32_16x16x32_bf16 v[90:93], v[154:157], v[212:215], v[90:93]
	v_mfma_f32_16x16x32_bf16 v[82:85], v[146:149], v[220:223], v[82:85]
	v_mfma_f32_16x16x32_bf16 v[74:77], v[154:157], v[220:223], v[74:77]
	s_setprio 0
	s_setprio 1
	v_mfma_f32_16x16x32_bf16 v[126:129], v[162:165], v[178:181], v[126:129]
	v_mfma_f32_16x16x32_bf16 v[118:121], v[170:173], v[178:181], v[118:121]
	v_mfma_f32_16x16x32_bf16 v[110:113], v[162:165], v[186:189], v[110:113]
	v_mfma_f32_16x16x32_bf16 v[102:105], v[170:173], v[186:189], v[102:105]
	v_mfma_f32_16x16x32_bf16 v[94:97], v[162:165], v[194:197], v[94:97]
	v_mfma_f32_16x16x32_bf16 v[86:89], v[170:173], v[194:197], v[86:89]
	v_mfma_f32_16x16x32_bf16 v[78:81], v[162:165], v[216:219], v[78:81]
	v_mfma_f32_16x16x32_bf16 v[70:73], v[170:173], v[216:219], v[70:73]
	v_mfma_f32_16x16x32_bf16 v[126:129], v[166:169], v[182:185], v[126:129]
	v_mfma_f32_16x16x32_bf16 v[118:121], v[174:177], v[182:185], v[118:121]
	v_mfma_f32_16x16x32_bf16 v[110:113], v[166:169], v[190:193], v[110:113]
	v_mfma_f32_16x16x32_bf16 v[102:105], v[174:177], v[190:193], v[102:105]
	v_mfma_f32_16x16x32_bf16 v[94:97], v[166:169], v[212:215], v[94:97]
	v_mfma_f32_16x16x32_bf16 v[86:89], v[174:177], v[212:215], v[86:89]
	v_mfma_f32_16x16x32_bf16 v[78:81], v[166:169], v[220:223], v[78:81]
	v_mfma_f32_16x16x32_bf16 v[70:73], v[174:177], v[220:223], v[70:73]
	s_setprio 0
	s_barrier
; #define PG8_STAGE(bufoff, gbase, voff) do { _Pragma("unroll") for (int _i = 0; _i < 2; ++_i) \
;         __builtin_amdgcn_global_load_lds((const unsigned*)((const char*)(gbase) + (voff)[_i]), (LAS unsigned*)(lds + (bufoff) + ldsw + _i * 8192), 16, 0, 0); } while (0)
; #define PG8_LDA(dst, b, h) do { _Pragma("unroll") for (int m = 0; m < 4; ++m) _Pragma("unroll") for (int k = 0; k < 2; ++k) dst[m][k] = *(const LAS bf16x8*)(lds + PG8_SA(b, h) + aoff + m * 2048 + k * 1024); } while (0)
; #define PG8_MMA(ai, bj, At, Bt) do { __builtin_amdgcn_s_setprio(1); _Pragma("unroll") for (int m = 0; m < 4; ++m) _Pragma("unroll") for (int n = 0; n < 2; ++n) _Pragma("unroll") for (int k = 0; k < 2; ++k) \
;         acc[ai][bj][m][n] = __builtin_amdgcn_mfma_f32_16x16x32_bf16(Bt[n][k], At[m][k], acc[ai][bj][m][n], 0, 0, 0); __builtin_amdgcn_s_setprio(0); } while (0)
; #define PG8_WAIT_V(n) asm volatile("s_waitcnt vmcnt(" #n ")" ::: "memory")
; #define PG8_WAIT_L(n) asm volatile("s_waitcnt lgkmcnt(" #n ")" ::: "memory")
; #define PG8_BAR __builtin_amdgcn_s_barrier()
; #define PG8_SCHED __builtin_amdgcn_sched_barrier(0)
; template <class Epi, class Sched>
; __device__ __forceinline__ void gemm_phase(LAS unsigned char* lds, const Gemm g, const Sched& S, const Epi& E) {
;     ...
;             PG8_LDA(At, 1, 1); PG8_STAGE(PG8_SB(1, 0), b3, voffB); PG8_STAGE(PG8_SB(1, 1), b3 + hstepB, voffB); PG8_STAGE(PG8_SA(1, 0), a3, voffA);
;             PG8_WAIT_V(8); PG8_WAIT_L(0); PG8_BAR; PG8_MMA(1, 0, At, B0); PG8_MMA(1, 1, At, B1); PG8_BAR; PG8_SCHED;
;         }
;         if (wr == 0) PG8_BAR;
	s_add_i32 s40, s60, s45
	v_lshl_add_u64 v[224:225], v[224:225], 0, s[36:37]
	s_mov_b32 m0, s40
	ds_read_b128 v[178:181], v161 offset:49152
	ds_read_b128 v[182:185], v161 offset:50176
	ds_read_b128 v[186:189], v161 offset:51200
	ds_read_b128 v[190:193], v161 offset:52224
	ds_read_b128 v[194:197], v161 offset:53248
	ds_read_b128 v[212:215], v161 offset:54272
	ds_read_b128 v[216:219], v161 offset:55296
	ds_read_b128 v[220:223], v161 offset:56320
	global_load_lds_dwordx4 v[224:225], off
	s_add_i32 m0, s40, 0x2000
	s_add_u32 s28, s28, 0x80080
	v_lshl_add_u64 v[224:225], v[226:227], 0, s[36:37]
	s_addc_u32 s29, s29, 0
	s_add_i32 s40, s61, s45
	global_load_lds_dwordx4 v[224:225], off
	v_lshl_add_u64 v[224:225], s[28:29], 0, v[4:5]
	s_mov_b32 m0, s40
	s_nop 0
	global_load_lds_dwordx4 v[224:225], off
	v_lshl_add_u64 v[224:225], s[28:29], 0, v[2:3]
	s_add_i32 m0, s40, 0x2000
	s_nop 0
	global_load_lds_dwordx4 v[224:225], off
	v_lshl_add_u64 v[224:225], v[228:229], 0, s[36:37]
	s_mov_b32 m0, s50
	s_nop 0
	global_load_lds_dwordx4 v[224:225], off
	v_lshl_add_u64 v[224:225], v[230:231], 0, s[36:37]
	s_mov_b32 m0, s51
	s_nop 0
	global_load_lds_dwordx4 v[224:225], off
	s_waitcnt vmcnt(8)
	s_waitcnt lgkmcnt(0)
	s_barrier
	s_setprio 1
	s_waitcnt lgkmcnt(0)
	v_mfma_f32_16x16x32_bf16 v[66:69], v[142:145], v[178:181], v[66:69]
	v_mfma_f32_16x16x32_bf16 v[58:61], v[150:153], v[178:181], v[58:61]
	v_mfma_f32_16x16x32_bf16 v[50:53], v[142:145], v[186:189], v[50:53]
	v_mfma_f32_16x16x32_bf16 v[42:45], v[150:153], v[186:189], v[42:45]
	v_mfma_f32_16x16x32_bf16 v[34:37], v[142:145], v[194:197], v[34:37]
	v_mfma_f32_16x16x32_bf16 v[26:29], v[150:153], v[194:197], v[26:29]
	v_mfma_f32_16x16x32_bf16 v[18:21], v[142:145], v[216:219], v[18:21]
	v_mfma_f32_16x16x32_bf16 v[10:13], v[150:153], v[216:219], v[10:13]
	v_mfma_f32_16x16x32_bf16 v[66:69], v[146:149], v[182:185], v[66:69]
	v_mfma_f32_16x16x32_bf16 v[58:61], v[154:157], v[182:185], v[58:61]
	v_mfma_f32_16x16x32_bf16 v[50:53], v[146:149], v[190:193], v[50:53]
	v_mfma_f32_16x16x32_bf16 v[42:45], v[154:157], v[190:193], v[42:45]
	v_mfma_f32_16x16x32_bf16 v[34:37], v[146:149], v[212:215], v[34:37]
	v_mfma_f32_16x16x32_bf16 v[26:29], v[154:157], v[212:215], v[26:29]
	v_mfma_f32_16x16x32_bf16 v[18:21], v[146:149], v[220:223], v[18:21]
	v_mfma_f32_16x16x32_bf16 v[10:13], v[154:157], v[220:223], v[10:13]
	s_setprio 0
	s_setprio 1
	v_mfma_f32_16x16x32_bf16 v[62:65], v[162:165], v[178:181], v[62:65]
	v_mfma_f32_16x16x32_bf16 v[54:57], v[170:173], v[178:181], v[54:57]
	v_mfma_f32_16x16x32_bf16 v[46:49], v[162:165], v[186:189], v[46:49]
	v_mfma_f32_16x16x32_bf16 v[38:41], v[170:173], v[186:189], v[38:41]
	v_mfma_f32_16x16x32_bf16 v[30:33], v[162:165], v[194:197], v[30:33]
	v_mfma_f32_16x16x32_bf16 v[22:25], v[170:173], v[194:197], v[22:25]
	v_mfma_f32_16x16x32_bf16 v[14:17], v[162:165], v[216:219], v[14:17]
	v_mfma_f32_16x16x32_bf16 v[6:9], v[170:173], v[216:219], v[6:9]
	v_mfma_f32_16x16x32_bf16 v[62:65], v[166:169], v[182:185], v[62:65]
	v_mfma_f32_16x16x32_bf16 v[54:57], v[174:177], v[182:185], v[54:57]
	v_mfma_f32_16x16x32_bf16 v[46:49], v[166:169], v[190:193], v[46:49]
	v_mfma_f32_16x16x32_bf16 v[38:41], v[174:177], v[190:193], v[38:41]
	v_mfma_f32_16x16x32_bf16 v[30:33], v[166:169], v[212:215], v[30:33]
	v_mfma_f32_16x16x32_bf16 v[22:25], v[174:177], v[212:215], v[22:25]
	v_mfma_f32_16x16x32_bf16 v[14:17], v[166:169], v[220:223], v[14:17]
	v_mfma_f32_16x16x32_bf16 v[6:9], v[174:177], v[220:223], v[6:9]
	s_setprio 0
	s_barrier
	s_add_i32 s59, s59, 2
	s_add_u32 s26, s26, 0x100
	s_addc_u32 s27, s27, 0
	s_add_u32 s57, s57, 0x100
	s_addc_u32 s58, s58, 0
	s_cmp_gt_u32 s59, 29
	s_cbranch_scc0 .LBB0_137
	s_andn2_b64 vcc, s[16:17], s[38:39]
	s_cbranch_vccz .LBB0_140
	s_barrier

; __device__ __forceinline__ unsigned pk2(float lo, float hi) { const f32x2 v = {lo, hi}; return __builtin_bit_cast(unsigned, __builtin_convertvector(v, bf16x2_t)); }
;     __device__ __forceinline__ void operator()(const f32x4 (&acc)[2][2][4][2], const Unit& u, int wr, int wc, int fr, int fq) const {
;     ...
; #pragma unroll
;         for (int ai = 0; ai < 2; ++ai)
; #pragma unroll
;             for (int m = 0; m < 4; ++m) {
;                 const float rs = rs8[ai][m], nrs = -1.44269504089f * rs;
;                 u32x4 w;
; #pragma unroll
;                 for (int n = 0; n < 2; ++n) { const f32x4 gq = acc[ai][0][m][n], uq = acc[ai][1][m][n];
; #pragma unroll
;                     for (int h = 0; h < 2; ++h) { const f32x2 gv = (f32x2){gq[2 * h], gq[2 * h + 1]}, uv = (f32x2){uq[2 * h], uq[2 * h + 1]};
;                         const f32x2 ea = gv * nrs; f32x2 e; e.x = __builtin_amdgcn_exp2f(ea.x); e.y = __builtin_amdgcn_exp2f(ea.y);
;                         const f32x2 d = e + 1.0f; f32x2 rc; rc.x = __builtin_amdgcn_rcpf(d.x); rc.y = __builtin_amdgcn_rcpf(d.y);
;                         const f32x2 o = (gv * uv) * (rc * (rs * rs));
;                         w[2 * n + h] = pk2(o.x, o.y); } }
;                 *(u32x4*)(O + (size_t)(row0 + ai * HALF + m * 16) * ldc + col0) = w; }
.Lmy_sw_join:
	v_lshl_or_b32 v162, s53, 7, v160
	v_mul_f32_e32 v164, 0xbfb8aa3b, v147
	v_pk_mul_f32 v[166:167], v[130:131], v[164:165] op_sel_hi:[1,0]
	v_pk_mul_f32 v[126:127], v[130:131], v[126:127]
	v_exp_f32_e32 v166, v166
	v_exp_f32_e32 v167, v167
	v_pk_mul_f32 v[130:131], v[132:133], v[164:165] op_sel_hi:[1,0]
	v_mul_f32_e32 v168, v147, v147
	v_exp_f32_e32 v130, v130
	v_exp_f32_e32 v131, v131
	v_pk_add_f32 v[166:167], v[166:167], 1.0 op_sel_hi:[1,0]
	v_pk_mul_f32 v[128:129], v[132:133], v[128:129]
	v_rcp_f32_e32 v166, v166
	v_rcp_f32_e32 v167, v167
	v_pk_add_f32 v[130:131], v[130:131], 1.0 op_sel_hi:[1,0]
	v_pk_mul_f32 v[118:119], v[122:123], v[118:119]
	v_rcp_f32_e32 v130, v130
	v_rcp_f32_e32 v131, v131
	v_pk_mul_f32 v[132:133], v[168:169], v[166:167] op_sel_hi:[0,1]
	v_pk_mul_f32 v[126:127], v[126:127], v[132:133]
	v_pk_mul_f32 v[132:133], v[122:123], v[164:165] op_sel_hi:[1,0]
	v_pk_mul_f32 v[130:131], v[168:169], v[130:131] op_sel_hi:[0,1]
	v_exp_f32_e32 v132, v132
	v_exp_f32_e32 v133, v133
	v_pk_mul_f32 v[128:129], v[128:129], v[130:131]
	v_pk_mul_f32 v[130:131], v[124:125], v[164:165] op_sel_hi:[1,0]
	v_cvt_pk_bf16_f32 v126, v126, v127
	v_exp_f32_e32 v130, v130
	v_exp_f32_e32 v131, v131
	v_cvt_pk_bf16_f32 v127, v128, v129
	v_pk_add_f32 v[128:129], v[132:133], 1.0 op_sel_hi:[1,0]
	v_pk_mul_f32 v[120:121], v[124:125], v[120:121]
	v_rcp_f32_e32 v128, v128
	v_rcp_f32_e32 v129, v129
	v_pk_add_f32 v[122:123], v[130:131], 1.0 op_sel_hi:[1,0]
	v_ashrrev_i32_e32 v163, 31, v162
	v_rcp_f32_e32 v122, v122
	v_rcp_f32_e32 v123, v123
	v_pk_mul_f32 v[124:125], v[168:169], v[128:129] op_sel_hi:[0,1]
	v_pk_mul_f32 v[118:119], v[118:119], v[124:125]
	v_mul_f32_e32 v124, 0xbfb8aa3b, v149
	v_cvt_pk_bf16_f32 v128, v118, v119
	v_pk_mul_f32 v[118:119], v[168:169], v[122:123] op_sel_hi:[0,1]
	v_pk_mul_f32 v[130:131], v[114:115], v[124:125] op_sel_hi:[1,0]
	v_pk_mul_f32 v[118:119], v[120:121], v[118:119]
	v_exp_f32_e32 v130, v130
	v_exp_f32_e32 v131, v131
	v_cvt_pk_bf16_f32 v129, v118, v119
	v_mov_b64_e32 v[118:119], s[12:13]
	v_pk_mul_f32 v[110:111], v[114:115], v[110:111]
	v_pk_mul_f32 v[114:115], v[116:117], v[124:125] op_sel_hi:[1,0]
	v_mad_i64_i32 v[122:123], s[26:27], v156, s1, v[118:119]
	v_lshlrev_b64 v[120:121], 1, v[162:163]
	v_exp_f32_e32 v114, v114
	v_exp_f32_e32 v115, v115
	v_lshl_add_u64 v[122:123], v[122:123], 0, v[120:121]
	global_store_dwordx4 v[122:123], v[126:129], off
	v_mul_f32_e32 v122, v149, v149
	v_pk_add_f32 v[114:115], v[114:115], 1.0 op_sel_hi:[1,0]
	v_pk_add_f32 v[126:127], v[130:131], 1.0 op_sel_hi:[1,0]
	v_rcp_f32_e32 v114, v114
	v_rcp_f32_e32 v126, v126
	v_rcp_f32_e32 v127, v127
	v_rcp_f32_e32 v115, v115
	v_pk_mul_f32 v[112:113], v[116:117], v[112:113]
	v_pk_mul_f32 v[102:103], v[106:107], v[102:103]
	v_pk_mul_f32 v[116:117], v[122:123], v[126:127] op_sel_hi:[0,1]
	v_pk_mul_f32 v[110:111], v[110:111], v[116:117]
	v_pk_mul_f32 v[116:117], v[106:107], v[124:125] op_sel_hi:[1,0]
	v_pk_mul_f32 v[114:115], v[122:123], v[114:115] op_sel_hi:[0,1]
	v_exp_f32_e32 v116, v116
	v_exp_f32_e32 v117, v117
	v_pk_mul_f32 v[112:113], v[112:113], v[114:115]
	v_pk_mul_f32 v[114:115], v[108:109], v[124:125] op_sel_hi:[1,0]
	v_cvt_pk_bf16_f32 v110, v110, v111
	v_exp_f32_e32 v114, v114
	v_exp_f32_e32 v115, v115
	v_cvt_pk_bf16_f32 v111, v112, v113
	v_pk_add_f32 v[112:113], v[116:117], 1.0 op_sel_hi:[1,0]
	v_pk_mul_f32 v[104:105], v[108:109], v[104:105]
	v_rcp_f32_e32 v112, v112
	v_rcp_f32_e32 v113, v113
	v_pk_add_f32 v[106:107], v[114:115], 1.0 op_sel_hi:[1,0]
	v_pk_mul_f32 v[94:95], v[98:99], v[94:95]
	v_rcp_f32_e32 v106, v106
	v_rcp_f32_e32 v107, v107
	v_pk_mul_f32 v[108:109], v[122:123], v[112:113] op_sel_hi:[0,1]
	v_pk_mul_f32 v[102:103], v[102:103], v[108:109]
	v_pk_mul_f32 v[96:97], v[100:101], v[96:97]
	v_cvt_pk_bf16_f32 v112, v102, v103
	v_pk_mul_f32 v[102:103], v[122:123], v[106:107] op_sel_hi:[0,1]
	v_pk_mul_f32 v[102:103], v[104:105], v[102:103]
	v_mul_f32_e32 v104, 0xbfb8aa3b, v151
	v_pk_mul_f32 v[106:107], v[98:99], v[104:105] op_sel_hi:[1,0]
	v_pk_mul_f32 v[98:99], v[100:101], v[104:105] op_sel_hi:[1,0]
	v_exp_f32_e32 v106, v106
	v_exp_f32_e32 v107, v107
	v_exp_f32_e32 v98, v98
	v_exp_f32_e32 v99, v99
	v_cvt_pk_bf16_f32 v113, v102, v103
	v_pk_add_f32 v[106:107], v[106:107], 1.0 op_sel_hi:[1,0]
	v_mad_i64_i32 v[102:103], s[26:27], v154, s1, v[118:119]
	v_rcp_f32_e32 v106, v106
	v_rcp_f32_e32 v107, v107
	v_pk_add_f32 v[98:99], v[98:99], 1.0 op_sel_hi:[1,0]
	v_lshl_add_u64 v[102:103], v[102:103], 0, v[120:121]
	v_rcp_f32_e32 v98, v98
	v_rcp_f32_e32 v99, v99
	global_store_dwordx4 v[102:103], v[110:113], off
	v_mul_f32_e32 v102, v151, v151
	v_pk_mul_f32 v[100:101], v[102:103], v[106:107] op_sel_hi:[0,1]
	v_pk_mul_f32 v[94:95], v[94:95], v[100:101]
	v_pk_mul_f32 v[100:101], v[90:91], v[104:105] op_sel_hi:[1,0]
	v_pk_mul_f32 v[98:99], v[102:103], v[98:99] op_sel_hi:[0,1]
	v_exp_f32_e32 v100, v100
	v_exp_f32_e32 v101, v101
	v_pk_mul_f32 v[96:97], v[96:97], v[98:99]
	v_pk_mul_f32 v[98:99], v[92:93], v[104:105] op_sel_hi:[1,0]
	v_cvt_pk_bf16_f32 v94, v94, v95
	v_exp_f32_e32 v98, v98
	v_exp_f32_e32 v99, v99
	v_cvt_pk_bf16_f32 v95, v96, v97
	v_pk_add_f32 v[96:97], v[100:101], 1.0 op_sel_hi:[1,0]
	v_pk_mul_f32 v[86:87], v[90:91], v[86:87]
	v_rcp_f32_e32 v96, v96
	v_rcp_f32_e32 v97, v97
	v_pk_add_f32 v[90:91], v[98:99], 1.0 op_sel_hi:[1,0]
	v_pk_mul_f32 v[88:89], v[92:93], v[88:89]
	v_rcp_f32_e32 v90, v90
	v_rcp_f32_e32 v91, v91
	v_pk_mul_f32 v[92:93], v[102:103], v[96:97] op_sel_hi:[0,1]
	v_pk_mul_f32 v[86:87], v[86:87], v[92:93]
	v_pk_mul_f32 v[78:79], v[82:83], v[78:79]
	v_cvt_pk_bf16_f32 v96, v86, v87
	v_pk_mul_f32 v[86:87], v[102:103], v[90:91] op_sel_hi:[0,1]
; __device__ __forceinline__ unsigned pk2(float lo, float hi) { const f32x2 v = {lo, hi}; return __builtin_bit_cast(unsigned, __builtin_convertvector(v, bf16x2_t)); }
;     __device__ __forceinline__ void operator()(const f32x4 (&acc)[2][2][4][2], const Unit& u, int wr, int wc, int fr, int fq) const {
;     ...
; #pragma unroll
;         for (int ai = 0; ai < 2; ++ai)
; #pragma unroll
;             for (int m = 0; m < 4; ++m) {
;                 const float rs = rs8[ai][m], nrs = -1.44269504089f * rs;
;                 u32x4 w;
; #pragma unroll
;                 for (int n = 0; n < 2; ++n) { const f32x4 gq = acc[ai][0][m][n], uq = acc[ai][1][m][n];
; #pragma unroll
;                     for (int h = 0; h < 2; ++h) { const f32x2 gv = (f32x2){gq[2 * h], gq[2 * h + 1]}, uv = (f32x2){uq[2 * h], uq[2 * h + 1]};
;                         const f32x2 ea = gv * nrs; f32x2 e; e.x = __builtin_amdgcn_exp2f(ea.x); e.y = __builtin_amdgcn_exp2f(ea.y);
;                         const f32x2 d = e + 1.0f; f32x2 rc; rc.x = __builtin_amdgcn_rcpf(d.x); rc.y = __builtin_amdgcn_rcpf(d.y);
;                         const f32x2 o = (gv * uv) * (rc * (rs * rs));
;                         w[2 * n + h] = pk2(o.x, o.y); } }
;                 *(u32x4*)(O + (size_t)(row0 + ai * HALF + m * 16) * ldc + col0) = w; }
	v_pk_mul_f32 v[86:87], v[88:89], v[86:87]
	v_mul_f32_e32 v88, 0xbfb8aa3b, v153
	v_pk_mul_f32 v[90:91], v[82:83], v[88:89] op_sel_hi:[1,0]
	v_pk_mul_f32 v[82:83], v[84:85], v[88:89] op_sel_hi:[1,0]
	v_exp_f32_e32 v90, v90
	v_exp_f32_e32 v91, v91
	v_exp_f32_e32 v82, v82
	v_exp_f32_e32 v83, v83
	v_cvt_pk_bf16_f32 v97, v86, v87
	v_pk_add_f32 v[90:91], v[90:91], 1.0 op_sel_hi:[1,0]
	v_mad_i64_i32 v[86:87], s[26:27], v152, s1, v[118:119]
	v_rcp_f32_e32 v90, v90
	v_rcp_f32_e32 v91, v91
	v_pk_add_f32 v[82:83], v[82:83], 1.0 op_sel_hi:[1,0]
	v_lshl_add_u64 v[86:87], v[86:87], 0, v[120:121]
	v_rcp_f32_e32 v82, v82
	v_rcp_f32_e32 v83, v83
	global_store_dwordx4 v[86:87], v[94:97], off
	v_mul_f32_e32 v86, v153, v153
	v_pk_mul_f32 v[80:81], v[84:85], v[80:81]
	v_pk_mul_f32 v[84:85], v[86:87], v[90:91] op_sel_hi:[0,1]
	v_pk_mul_f32 v[78:79], v[78:79], v[84:85]
	v_pk_mul_f32 v[84:85], v[74:75], v[88:89] op_sel_hi:[1,0]
	v_pk_mul_f32 v[82:83], v[86:87], v[82:83] op_sel_hi:[0,1]
	v_exp_f32_e32 v84, v84
	v_exp_f32_e32 v85, v85
	v_pk_mul_f32 v[80:81], v[80:81], v[82:83]
	v_pk_mul_f32 v[82:83], v[76:77], v[88:89] op_sel_hi:[1,0]
	v_cvt_pk_bf16_f32 v78, v78, v79
	v_exp_f32_e32 v82, v82
	v_exp_f32_e32 v83, v83
	v_cvt_pk_bf16_f32 v79, v80, v81
	v_pk_add_f32 v[80:81], v[84:85], 1.0 op_sel_hi:[1,0]
	v_pk_mul_f32 v[70:71], v[74:75], v[70:71]
	v_rcp_f32_e32 v80, v80
	v_rcp_f32_e32 v81, v81
	v_pk_add_f32 v[74:75], v[82:83], 1.0 op_sel_hi:[1,0]
	v_pk_mul_f32 v[72:73], v[76:77], v[72:73]
	v_rcp_f32_e32 v74, v74
	v_rcp_f32_e32 v75, v75
	v_pk_mul_f32 v[76:77], v[86:87], v[80:81] op_sel_hi:[0,1]
	v_pk_mul_f32 v[70:71], v[70:71], v[76:77]
	v_pk_mul_f32 v[62:63], v[66:67], v[62:63]
	v_cvt_pk_bf16_f32 v80, v70, v71
	v_pk_mul_f32 v[70:71], v[86:87], v[74:75] op_sel_hi:[0,1]
	v_pk_mul_f32 v[70:71], v[72:73], v[70:71]
	v_mul_f32_e32 v72, 0xbfb8aa3b, v155
	v_pk_mul_f32 v[74:75], v[66:67], v[72:73] op_sel_hi:[1,0]
	v_pk_mul_f32 v[66:67], v[68:69], v[72:73] op_sel_hi:[1,0]
	v_exp_f32_e32 v74, v74
	v_exp_f32_e32 v75, v75
	v_exp_f32_e32 v66, v66
	v_exp_f32_e32 v67, v67
	v_cvt_pk_bf16_f32 v81, v70, v71
	v_pk_add_f32 v[74:75], v[74:75], 1.0 op_sel_hi:[1,0]
	v_mad_i64_i32 v[70:71], s[26:27], v150, s1, v[118:119]
	v_rcp_f32_e32 v74, v74
	v_rcp_f32_e32 v75, v75
	v_pk_add_f32 v[66:67], v[66:67], 1.0 op_sel_hi:[1,0]
	v_lshl_add_u64 v[70:71], v[70:71], 0, v[120:121]
	v_rcp_f32_e32 v66, v66
	v_rcp_f32_e32 v67, v67
	global_store_dwordx4 v[70:71], v[78:81], off
	v_mul_f32_e32 v70, v155, v155
	v_pk_mul_f32 v[64:65], v[68:69], v[64:65]
	v_pk_mul_f32 v[68:69], v[70:71], v[74:75] op_sel_hi:[0,1]
	v_pk_mul_f32 v[62:63], v[62:63], v[68:69]
	v_pk_mul_f32 v[68:69], v[58:59], v[72:73] op_sel_hi:[1,0]
	v_pk_mul_f32 v[66:67], v[70:71], v[66:67] op_sel_hi:[0,1]
	v_exp_f32_e32 v68, v68
	v_exp_f32_e32 v69, v69
	v_pk_mul_f32 v[64:65], v[64:65], v[66:67]
	v_pk_mul_f32 v[66:67], v[60:61], v[72:73] op_sel_hi:[1,0]
	v_cvt_pk_bf16_f32 v62, v62, v63
	v_exp_f32_e32 v66, v66
	v_exp_f32_e32 v67, v67
	v_cvt_pk_bf16_f32 v63, v64, v65
	v_pk_add_f32 v[64:65], v[68:69], 1.0 op_sel_hi:[1,0]
	v_pk_mul_f32 v[54:55], v[58:59], v[54:55]
	v_rcp_f32_e32 v64, v64
	v_rcp_f32_e32 v65, v65
	v_pk_add_f32 v[58:59], v[66:67], 1.0 op_sel_hi:[1,0]
	v_pk_mul_f32 v[56:57], v[60:61], v[56:57]
	v_rcp_f32_e32 v58, v58
	v_rcp_f32_e32 v59, v59
	v_pk_mul_f32 v[60:61], v[70:71], v[64:65] op_sel_hi:[0,1]
	v_pk_mul_f32 v[54:55], v[54:55], v[60:61]
	v_pk_mul_f32 v[46:47], v[50:51], v[46:47]
	v_cvt_pk_bf16_f32 v64, v54, v55
	v_pk_mul_f32 v[54:55], v[70:71], v[58:59] op_sel_hi:[0,1]
	v_pk_mul_f32 v[54:55], v[56:57], v[54:55]
	v_mul_f32_e32 v56, 0xbfb8aa3b, v157
	v_pk_mul_f32 v[58:59], v[50:51], v[56:57] op_sel_hi:[1,0]
	v_pk_mul_f32 v[50:51], v[52:53], v[56:57] op_sel_hi:[1,0]
	v_exp_f32_e32 v58, v58
	v_exp_f32_e32 v59, v59
	v_exp_f32_e32 v50, v50
	v_exp_f32_e32 v51, v51
	v_cvt_pk_bf16_f32 v65, v54, v55
	v_pk_add_f32 v[58:59], v[58:59], 1.0 op_sel_hi:[1,0]
	v_mad_i64_i32 v[54:55], s[26:27], v148, s1, v[118:119]
	v_rcp_f32_e32 v58, v58
	v_rcp_f32_e32 v59, v59
	v_pk_add_f32 v[50:51], v[50:51], 1.0 op_sel_hi:[1,0]
	v_lshl_add_u64 v[54:55], v[54:55], 0, v[120:121]
	v_rcp_f32_e32 v50, v50
	v_rcp_f32_e32 v51, v51
	global_store_dwordx4 v[54:55], v[62:65], off
	v_mul_f32_e32 v54, v157, v157
	v_pk_mul_f32 v[48:49], v[52:53], v[48:49]
	v_pk_mul_f32 v[52:53], v[54:55], v[58:59] op_sel_hi:[0,1]
	v_pk_mul_f32 v[46:47], v[46:47], v[52:53]
	v_pk_mul_f32 v[52:53], v[42:43], v[56:57] op_sel_hi:[1,0]
	v_pk_mul_f32 v[50:51], v[54:55], v[50:51] op_sel_hi:[0,1]
	v_exp_f32_e32 v52, v52
	v_exp_f32_e32 v53, v53
; __device__ __forceinline__ unsigned pk2(float lo, float hi) { const f32x2 v = {lo, hi}; return __builtin_bit_cast(unsigned, __builtin_convertvector(v, bf16x2_t)); }
; #define PG8_BAR __builtin_amdgcn_s_barrier()
;     __device__ __forceinline__ void operator()(const f32x4 (&acc)[2][2][4][2], const Unit& u, int wr, int wc, int fr, int fq) const {
;     ...
; #pragma unroll
;         for (int ai = 0; ai < 2; ++ai)
; #pragma unroll
;             for (int m = 0; m < 4; ++m) {
;                 const float rs = rs8[ai][m], nrs = -1.44269504089f * rs;
;                 u32x4 w;
; #pragma unroll
;                 for (int n = 0; n < 2; ++n) { const f32x4 gq = acc[ai][0][m][n], uq = acc[ai][1][m][n];
; #pragma unroll
;                     for (int h = 0; h < 2; ++h) { const f32x2 gv = (f32x2){gq[2 * h], gq[2 * h + 1]}, uv = (f32x2){uq[2 * h], uq[2 * h + 1]};
;                         const f32x2 ea = gv * nrs; f32x2 e; e.x = __builtin_amdgcn_exp2f(ea.x); e.y = __builtin_amdgcn_exp2f(ea.y);
;                         const f32x2 d = e + 1.0f; f32x2 rc; rc.x = __builtin_amdgcn_rcpf(d.x); rc.y = __builtin_amdgcn_rcpf(d.y);
;                         const f32x2 o = (gv * uv) * (rc * (rs * rs));
;                         w[2 * n + h] = pk2(o.x, o.y); } }
;                 *(u32x4*)(O + (size_t)(row0 + ai * HALF + m * 16) * ldc + col0) = w; }
; template <class Epi, class Sched>
; __device__ __forceinline__ void gemm_phase(LAS unsigned char* lds, const Gemm g, const Sched& S, const Epi& E) {
;     ...
;         if (wr == 0) PG8_BAR;
;         if constexpr (!Epi::AFTER_DRAIN) { E(acc, cur, wr, wc, fr, fq); S.done(cur); }
;         if (!has_next) break;
; #pragma unroll
;         for (int a = 0; a < 2; ++a)
; #pragma unroll
;             for (int b = 0; b < 2; ++b)
; #pragma unroll
;                 for (int m = 0; m < 4; ++m)
; #pragma unroll
;                     for (int n = 0; n < 2; ++n) acc[a][b][m][n] = (f32x4){0.f, 0.f, 0.f, 0.f};
;         cur = nxt; cA = nA; cB = nB; ++ui;
;         if (wr == 1) PG8_BAR;
	v_pk_mul_f32 v[48:49], v[48:49], v[50:51]
	v_pk_mul_f32 v[50:51], v[44:45], v[56:57] op_sel_hi:[1,0]
	v_cvt_pk_bf16_f32 v46, v46, v47
	v_exp_f32_e32 v50, v50
	v_exp_f32_e32 v51, v51
	v_cvt_pk_bf16_f32 v47, v48, v49
	v_pk_add_f32 v[48:49], v[52:53], 1.0 op_sel_hi:[1,0]
	v_pk_mul_f32 v[38:39], v[42:43], v[38:39]
	v_rcp_f32_e32 v48, v48
	v_rcp_f32_e32 v49, v49
	v_pk_add_f32 v[42:43], v[50:51], 1.0 op_sel_hi:[1,0]
	v_pk_mul_f32 v[40:41], v[44:45], v[40:41]
	v_rcp_f32_e32 v42, v42
	v_rcp_f32_e32 v43, v43
	v_pk_mul_f32 v[44:45], v[54:55], v[48:49] op_sel_hi:[0,1]
	v_pk_mul_f32 v[38:39], v[38:39], v[44:45]
	v_pk_mul_f32 v[30:31], v[34:35], v[30:31]
	v_cvt_pk_bf16_f32 v48, v38, v39
	v_pk_mul_f32 v[38:39], v[54:55], v[42:43] op_sel_hi:[0,1]
	v_pk_mul_f32 v[38:39], v[40:41], v[38:39]
	v_mul_f32_e32 v40, 0xbfb8aa3b, v145
	v_pk_mul_f32 v[42:43], v[34:35], v[40:41] op_sel_hi:[1,0]
	v_pk_mul_f32 v[34:35], v[36:37], v[40:41] op_sel_hi:[1,0]
	v_exp_f32_e32 v42, v42
	v_exp_f32_e32 v43, v43
	v_exp_f32_e32 v34, v34
	v_exp_f32_e32 v35, v35
	v_cvt_pk_bf16_f32 v49, v38, v39
	v_pk_add_f32 v[42:43], v[42:43], 1.0 op_sel_hi:[1,0]
	v_mad_i64_i32 v[38:39], s[26:27], v146, s1, v[118:119]
	v_rcp_f32_e32 v42, v42
	v_rcp_f32_e32 v43, v43
	v_pk_add_f32 v[34:35], v[34:35], 1.0 op_sel_hi:[1,0]
	v_lshl_add_u64 v[38:39], v[38:39], 0, v[120:121]
	v_rcp_f32_e32 v34, v34
	v_rcp_f32_e32 v35, v35
	global_store_dwordx4 v[38:39], v[46:49], off
	v_mul_f32_e32 v38, v145, v145
	v_pk_mul_f32 v[32:33], v[36:37], v[32:33]
	v_pk_mul_f32 v[36:37], v[38:39], v[42:43] op_sel_hi:[0,1]
	v_pk_mul_f32 v[30:31], v[30:31], v[36:37]
	v_pk_mul_f32 v[36:37], v[26:27], v[40:41] op_sel_hi:[1,0]
	v_pk_mul_f32 v[34:35], v[38:39], v[34:35] op_sel_hi:[0,1]
	v_exp_f32_e32 v36, v36
	v_exp_f32_e32 v37, v37
	v_pk_mul_f32 v[32:33], v[32:33], v[34:35]
	v_pk_mul_f32 v[34:35], v[28:29], v[40:41] op_sel_hi:[1,0]
	v_cvt_pk_bf16_f32 v30, v30, v31
	v_exp_f32_e32 v34, v34
	v_exp_f32_e32 v35, v35
	v_cvt_pk_bf16_f32 v31, v32, v33
	v_pk_add_f32 v[32:33], v[36:37], 1.0 op_sel_hi:[1,0]
	v_pk_mul_f32 v[22:23], v[26:27], v[22:23]
	v_rcp_f32_e32 v32, v32
	v_rcp_f32_e32 v33, v33
	v_pk_add_f32 v[26:27], v[34:35], 1.0 op_sel_hi:[1,0]
	v_pk_mul_f32 v[24:25], v[28:29], v[24:25]
	v_rcp_f32_e32 v26, v26
	v_rcp_f32_e32 v27, v27
	v_pk_mul_f32 v[28:29], v[38:39], v[32:33] op_sel_hi:[0,1]
	v_pk_mul_f32 v[22:23], v[22:23], v[28:29]
	v_pk_mul_f32 v[14:15], v[18:19], v[14:15]
	v_cvt_pk_bf16_f32 v32, v22, v23
	v_pk_mul_f32 v[22:23], v[38:39], v[26:27] op_sel_hi:[0,1]
	v_pk_mul_f32 v[22:23], v[24:25], v[22:23]
	v_mul_f32_e32 v24, 0xbfb8aa3b, v143
	v_pk_mul_f32 v[26:27], v[18:19], v[24:25] op_sel_hi:[1,0]
	v_pk_mul_f32 v[18:19], v[20:21], v[24:25] op_sel_hi:[1,0]
	v_exp_f32_e32 v26, v26
	v_exp_f32_e32 v27, v27
	v_exp_f32_e32 v18, v18
	v_exp_f32_e32 v19, v19
	v_cvt_pk_bf16_f32 v33, v22, v23
	v_pk_add_f32 v[26:27], v[26:27], 1.0 op_sel_hi:[1,0]
	v_mad_i64_i32 v[22:23], s[26:27], v144, s1, v[118:119]
	v_rcp_f32_e32 v26, v26
	v_rcp_f32_e32 v27, v27
	v_pk_add_f32 v[18:19], v[18:19], 1.0 op_sel_hi:[1,0]
	v_lshl_add_u64 v[22:23], v[22:23], 0, v[120:121]
	v_rcp_f32_e32 v18, v18
	v_rcp_f32_e32 v19, v19
	global_store_dwordx4 v[22:23], v[30:33], off
	v_mul_f32_e32 v22, v143, v143
	v_pk_mul_f32 v[16:17], v[20:21], v[16:17]
	v_pk_mul_f32 v[20:21], v[22:23], v[26:27] op_sel_hi:[0,1]
	v_pk_mul_f32 v[14:15], v[14:15], v[20:21]
	v_pk_mul_f32 v[20:21], v[10:11], v[24:25] op_sel_hi:[1,0]
	v_pk_mul_f32 v[18:19], v[22:23], v[18:19] op_sel_hi:[0,1]
	v_exp_f32_e32 v20, v20
	v_exp_f32_e32 v21, v21
	v_pk_mul_f32 v[16:17], v[16:17], v[18:19]
	v_pk_mul_f32 v[18:19], v[12:13], v[24:25] op_sel_hi:[1,0]
	v_cvt_pk_bf16_f32 v14, v14, v15
	v_exp_f32_e32 v18, v18
	v_exp_f32_e32 v19, v19
	v_cvt_pk_bf16_f32 v15, v16, v17
	v_pk_add_f32 v[16:17], v[20:21], 1.0 op_sel_hi:[1,0]
	v_pk_mul_f32 v[6:7], v[10:11], v[6:7]
	v_rcp_f32_e32 v16, v16
	v_rcp_f32_e32 v17, v17
	v_pk_add_f32 v[10:11], v[18:19], 1.0 op_sel_hi:[1,0]
	v_pk_mul_f32 v[8:9], v[12:13], v[8:9]
	v_rcp_f32_e32 v10, v10
	v_rcp_f32_e32 v11, v11
	v_pk_mul_f32 v[12:13], v[22:23], v[16:17] op_sel_hi:[0,1]
	v_pk_mul_f32 v[6:7], v[6:7], v[12:13]
	s_andn2_b64 vcc, exec, s[38:39]
	v_cvt_pk_bf16_f32 v16, v6, v7
	v_pk_mul_f32 v[6:7], v[22:23], v[10:11] op_sel_hi:[0,1]
	v_pk_mul_f32 v[6:7], v[8:9], v[6:7]
	s_nop 0
	v_cvt_pk_bf16_f32 v17, v6, v7
	v_mad_i64_i32 v[6:7], s[26:27], v142, s1, v[118:119]
	v_lshl_add_u64 v[6:7], v[6:7], 0, v[120:121]
	s_mov_b64 s[26:27], -1
	global_store_dwordx4 v[6:7], v[14:17], off
	s_cbranch_vccnz .LBB0_133
	s_branch .LBB0_132

; #define PG8_STAGE(bufoff, gbase, voff) do { _Pragma("unroll") for (int _i = 0; _i < 2; ++_i) \
;         __builtin_amdgcn_global_load_lds((const unsigned*)((const char*)(gbase) + (voff)[_i]), (LAS unsigned*)(lds + (bufoff) + ldsw + _i * 8192), 16, 0, 0); } while (0)
; #define PG8_WAIT_V(n) asm volatile("s_waitcnt vmcnt(" #n ")" ::: "memory")
; #define PG8_BAR __builtin_amdgcn_s_barrier()
; template <class Epi, class Sched>
; __device__ __forceinline__ void gemm_phase(LAS unsigned char* lds, const Gemm g, const Sched& S, const Epi& E) {
;     ...
;     f32x4 acc[2][2][4][2];
; #pragma unroll
;     for (int a = 0; a < 2; ++a)
; #pragma unroll
;         for (int b = 0; b < 2; ++b)
; #pragma unroll
;             for (int m = 0; m < 4; ++m)
; #pragma unroll
;                 for (int n = 0; n < 2; ++n) acc[a][b][m][n] = (f32x4){0.f, 0.f, 0.f, 0.f};
;     bf16x8 At[4][2], B0[2][2], B1[2][2];
;     const char* cA = (const char*)g.A + (size_t)cur.pm * tstepA + (size_t)cur.ka * 2; const char* cB = (const char*)g.Bt + (size_t)cur.pn * tstepB;
;     S.a_ready(cur);
;     PG8_STAGE(PG8_SB(0, 0), cB, voffB); PG8_STAGE(PG8_SB(0, 1), cB + hstepB, voffB); PG8_STAGE(PG8_SA(0, 0), cA, voffA); PG8_STAGE(PG8_SA(0, 1), cA + hstepA, voffA);
;     if (wr == 1) PG8_BAR;
;     PG8_WAIT_V(2); PG8_BAR;
;     PG8_STAGE(PG8_SB(1, 0), cB + kstep, voffB); PG8_STAGE(PG8_SA(1, 0), cA + kstep, voffA); PG8_STAGE(PG8_SB(1, 1), cB + hstepB + kstep, voffB);
;     PG8_WAIT_V(6); PG8_BAR;
.LBB0_267:
	v_lshl_add_u64 v[14:15], s[24:25], 0, v[4:5]
	v_mov_b32_e32 v3, v5
	v_and_b32_e32 v142, 15, v143
	v_and_b32_e32 v22, 48, v143
	v_lshlrev_b32_e32 v23, 2, v143
	v_lshl_add_u64 v[16:17], s[24:25], 0, v[2:3]
	s_and_b32 s48, s44, 3
	v_lshl_or_b32 v22, v142, 6, v22
	s_lshl_b32 s4, s47, 13
	v_and_b32_e32 v23, 32, v23
	s_add_i32 m0, s50, 0x18000
	v_lshl_add_u64 v[14:15], v[14:15], 0, s[36:37]
	v_lshl_add_u64 v[18:19], s[20:21], 0, v[4:5]
	v_bitop3_b32 v24, v22, s4, v23 bitop3:0xde
	s_lshl_b32 s4, s48, 12
	s_waitcnt vmcnt(2)
	s_barrier
	global_load_lds_dwordx4 v[14:15], off
	v_lshl_add_u64 v[14:15], v[16:17], 0, s[36:37]
	s_add_i32 m0, s50, 0x1a000
	s_add_i32 s54, s50, 0x8000
	s_add_i32 s55, s50, 0xa000
	v_lshl_add_u64 v[20:21], s[20:21], 0, v[2:3]
	v_bitop3_b32 v144, v22, s4, v23 bitop3:0xde
	global_load_lds_dwordx4 v[14:15], off
	v_lshl_add_u64 v[14:15], v[18:19], 0, s[36:37]
	s_mov_b32 m0, s54
	s_add_u32 s4, s24, 0x158080
	global_load_lds_dwordx4 v[14:15], off
	v_lshl_add_u64 v[14:15], v[20:21], 0, s[36:37]
	s_mov_b32 m0, s55
	s_addc_u32 s5, s25, 0
	global_load_lds_dwordx4 v[14:15], off
	s_add_i32 m0, s50, 0x1c000
	v_lshl_add_u64 v[14:15], s[4:5], 0, v[4:5]
	global_load_lds_dwordx4 v[14:15], off
	v_lshl_add_u64 v[14:15], s[4:5], 0, v[2:3]
	s_add_i32 m0, s50, 0x1e000
	s_movk_i32 s10, 0x1580
	global_load_lds_dwordx4 v[14:15], off
	v_lshrrev_b32_e32 v11, 1, v11
	v_mul_lo_u32 v10, v10, s10
	s_mov_b32 s22, 0x15800
	v_mad_u64_u32 v[10:11], s[4:5], v11, s22, v[10:11]
	v_or_b32_e32 v10, v10, v12
	v_add_lshl_u32 v134, v10, v13, 1
	v_lshrrev_b32_e32 v10, 1, v6
	v_mul_lo_u32 v6, v7, s10
	v_mad_u64_u32 v[6:7], s[4:5], v10, s22, v[6:7]
	s_waitcnt vmcnt(6)
	v_or_b32_e32 v6, v6, v8
	s_cmpk_lt_u32 s45, 0x100
	v_add_lshl_u32 v136, v6, v9, 1
	v_mov_b32_e32 v6, 0
	v_readlane_b32 s4, v254, 13
	s_cselect_b64 s[18:19], -1, 0
	v_mov_b32_e32 v135, v5
	v_mov_b32_e32 v137, v5
	s_mov_b32 s59, 0
	v_add_u32_e32 v145, 0, v24
	s_mov_b32 s10, s4
	v_readlane_b32 s46, v253, 61
	v_mov_b32_e32 v7, v6
	v_mov_b32_e32 v8, v6
	v_mov_b32_e32 v9, v6
	v_mov_b32_e32 v10, v6
	v_mov_b32_e32 v11, v6
	v_mov_b32_e32 v12, v6
	v_mov_b32_e32 v13, v6
	v_mov_b32_e32 v14, v6
	v_mov_b32_e32 v15, v6
	v_mov_b32_e32 v16, v6
	v_mov_b32_e32 v17, v6
	v_mov_b32_e32 v18, v6
	v_mov_b32_e32 v19, v6
	v_mov_b32_e32 v20, v6
	v_mov_b32_e32 v21, v6
	v_mov_b32_e32 v22, v6
	v_mov_b32_e32 v23, v6
	v_mov_b32_e32 v24, v6
	v_mov_b32_e32 v25, v6
	v_mov_b32_e32 v30, v6
	v_mov_b32_e32 v31, v6
	v_mov_b32_e32 v32, v6
	v_mov_b32_e32 v33, v6
	v_mov_b32_e32 v38, v6
	v_mov_b32_e32 v39, v6
	v_mov_b32_e32 v40, v6
	v_mov_b32_e32 v41, v6
	v_mov_b32_e32 v46, v6
	v_mov_b32_e32 v47, v6
	v_mov_b32_e32 v48, v6
	v_mov_b32_e32 v49, v6
	v_mov_b32_e32 v26, v6
	v_mov_b32_e32 v27, v6
	v_mov_b32_e32 v28, v6
	v_mov_b32_e32 v29, v6
	v_mov_b32_e32 v34, v6
	v_mov_b32_e32 v35, v6
	v_mov_b32_e32 v36, v6
	v_mov_b32_e32 v37, v6
	v_mov_b32_e32 v42, v6
	v_mov_b32_e32 v43, v6
	v_mov_b32_e32 v44, v6
	v_mov_b32_e32 v45, v6
	v_mov_b32_e32 v50, v6
	v_mov_b32_e32 v51, v6
	v_mov_b32_e32 v52, v6
	v_mov_b32_e32 v53, v6
	v_mov_b32_e32 v54, v6
	v_mov_b32_e32 v55, v6
	v_mov_b32_e32 v56, v6
	v_mov_b32_e32 v57, v6
	v_mov_b32_e32 v58, v6
	v_mov_b32_e32 v59, v6
	v_mov_b32_e32 v60, v6
	v_mov_b32_e32 v61, v6
	v_mov_b32_e32 v62, v6
	v_mov_b32_e32 v63, v6
	v_mov_b32_e32 v64, v6
	v_mov_b32_e32 v65, v6
	v_mov_b32_e32 v66, v6
	v_mov_b32_e32 v67, v6
	v_mov_b32_e32 v68, v6
	v_mov_b32_e32 v69, v6
	v_mov_b32_e32 v70, v6
	v_mov_b32_e32 v71, v6
	v_mov_b32_e32 v72, v6
	v_mov_b32_e32 v73, v6
	v_mov_b32_e32 v74, v6
	v_mov_b32_e32 v75, v6
	v_mov_b32_e32 v76, v6
	v_mov_b32_e32 v77, v6
	v_mov_b32_e32 v78, v6
	v_mov_b32_e32 v79, v6
	v_mov_b32_e32 v80, v6
	v_mov_b32_e32 v81, v6
	v_mov_b32_e32 v82, v6
	v_mov_b32_e32 v83, v6
	v_mov_b32_e32 v84, v6
	v_mov_b32_e32 v85, v6
	v_mov_b32_e32 v86, v6
	v_mov_b32_e32 v87, v6
	v_mov_b32_e32 v88, v6
	v_mov_b32_e32 v89, v6
	v_mov_b32_e32 v94, v6
	v_mov_b32_e32 v95, v6
	v_mov_b32_e32 v96, v6
	v_mov_b32_e32 v97, v6
	v_mov_b32_e32 v102, v6
	v_mov_b32_e32 v103, v6
	v_mov_b32_e32 v104, v6
	v_mov_b32_e32 v105, v6
	v_mov_b32_e32 v114, v6
	v_mov_b32_e32 v115, v6
	v_mov_b32_e32 v116, v6
	v_mov_b32_e32 v117, v6
	v_mov_b32_e32 v90, v6
	v_mov_b32_e32 v91, v6
	v_mov_b32_e32 v92, v6
	v_mov_b32_e32 v93, v6
	v_mov_b32_e32 v98, v6
	v_mov_b32_e32 v99, v6
	v_mov_b32_e32 v100, v6
	v_mov_b32_e32 v101, v6
	v_mov_b32_e32 v106, v6
	v_mov_b32_e32 v107, v6
	v_mov_b32_e32 v108, v6
	v_mov_b32_e32 v109, v6
	v_mov_b32_e32 v110, v6
	v_mov_b32_e32 v111, v6
	v_mov_b32_e32 v112, v6
	v_mov_b32_e32 v113, v6
	v_mov_b32_e32 v118, v6
	v_mov_b32_e32 v119, v6
	v_mov_b32_e32 v120, v6
	v_mov_b32_e32 v121, v6
	v_mov_b32_e32 v122, v6
	v_mov_b32_e32 v123, v6
	v_mov_b32_e32 v124, v6
	v_mov_b32_e32 v125, v6
	v_mov_b32_e32 v126, v6
	v_mov_b32_e32 v127, v6
	v_mov_b32_e32 v128, v6
	v_mov_b32_e32 v129, v6
	v_mov_b32_e32 v130, v6
	v_mov_b32_e32 v131, v6
	v_mov_b32_e32 v132, v6
	v_mov_b32_e32 v133, v6
	s_barrier
	s_branch .LBB0_270
	s_nop 0
	s_nop 0
	s_nop 0
	s_nop 0
	s_nop 0
	s_nop 0
	s_nop 0
	s_nop 0
	s_nop 0
	s_nop 0
	s_nop 0
	s_nop 0
	s_nop 0
	s_nop 0
	s_nop 0
	s_nop 0
	s_nop 0
	s_nop 0
	s_nop 0
	s_nop 0
	s_nop 0
	s_nop 0
	s_nop 0
	s_nop 0
	s_nop 0
	s_nop 0
	s_nop 0
	s_nop 0
	s_nop 0
	s_nop 0
	s_nop 0
	s_nop 0
	s_nop 0
